# rope table loads only on rope tiles; tile-start prefetch takes its pointers from register lanes (no scalar loads before the K-loop)
# speedup vs baseline: 1.0211x; 1.0013x over previous
; #define STAGE(P, BASE, br, kt) do { const char* _sb = (const char*)((BASE) + (long)(br) * K + (long)(kt) * G_BK); \
;     _Pragma("unroll") for (int _i = 0; _i < 2; ++_i) { \
;       __builtin_amdgcn_global_load_lds((glb_u32p)(_sb + (size_t)voff[_i]), \
;         (lds_u32p)((char*)(P) + tid * 16 + _i * 8192), 16, 0, 0); } } while (0)
; #define BAR __builtin_amdgcn_s_barrier()
; template <bool F16>
; DI void gemm256(const bf16_t* __restrict__ A, const bf16_t* __restrict__ Bt, int brow, int bcol, char* ldsc,
;                 f32x4 (&acc)[2][2][4][2]) {
;     ...
;   const int wid = tid >> 6, lane = tid & 63, wr = wid >> 2, wc = wid & 3, fr = lane & 15, fq = lane >> 4;
;   bf16x8 At[4][2], B0[2][2], B1[2][2];
;   constexpr int nt = K / G_BK;
;   unsigned voff[2];
; #pragma unroll
;   for (int i = 0; i < 2; ++i) { int r_, c_; stage_rc(tid * 16 + i * 8192, r_, c_); voff[i] = (unsigned)((r_ * K + c_) * 2); }
;   STAGE(SB(0, 0), Bt, bcol, 0); STAGE(SB(0, 1), Bt, bcol + G_HALF, 0); STAGE(SA(0, 0), A, brow, 0); STAGE(SA(0, 1), A, brow + G_HALF, 0);
;   if (wr == 1) BAR;
; DI void phaseA_tile(const Params& p0, int l, int ft, int mt, char* lds) {
;     ...
;   f32x4 bvA[2][4];
;   {
;     const float* bb = p.bias + (size_t)(l * 17 + modrow) * INW + n0 + wr * 64 + fq * 4;
; #pragma unroll
;     for (int ai = 0; ai < 2; ++ai)
; #pragma unroll
;       for (int m = 0; m < 4; ++m) bvA[ai][m] = *(const f32x4*)(bb + ai * 128 + m * 16);
;   }
;   float rstd[4];
; #pragma unroll
;   for (int gp = 0; gp < 2; ++gp) {
;     f32x4 sq[2][4];
; #pragma unroll
;     for (int n = 0; n < 2; ++n) {
;       const f32x4* sp = (const f32x4*)(p.ssq + (size_t)(m0 + tl[gp * 2 + n]) * 16);
; #pragma unroll
;       for (int q = 0; q < 4; ++q) sq[n][q] = sp[q];
;     }
; #pragma unroll
;     for (int n = 0; n < 2; ++n) {
;       float ss = 0.f;
; #pragma unroll
;       for (int q = 0; q < 4; ++q) ss += (sq[n][q][0] + sq[n][q][1]) + (sq[n][q][2] + sq[n][q][3]);
;       rstd[gp * 2 + n] = rsqrtf(ss * (1.f / DM) + EPS);
;     }
;   }
.LBB0_350:
	v_readlane_b32 s29, v255, 3
	v_readlane_b32 s30, v254, 61
	v_readlane_b32 s31, v254, 62
	v_readlane_b32 s34, v254, 63
	v_readlane_b32 s35, v255, 0
	s_lshr_b32 s69, s28, 3
	s_cmpk_lt_i32 s28, 0x80
	s_cselect_b32 s69, s69, 16
	s_mul_i32 s70, s29, 17
	s_add_i32 s69, s69, s70
	s_mul_hi_u32 s70, s69, 0x2c00
	s_mul_i32 s69, s69, 0x2c00
	s_lshl_b32 s71, s68, 10
	s_add_u32 s69, s69, s71
	s_addc_u32 s70, s70, 0
	v_lshlrev_b32_e32 v226, 4, v240
	v_lshrrev_b32_e32 v228, 6, v251
	v_lshl_add_u32 v227, v228, 11, v226
	s_nop 0
	v_readfirstlane_b32 s74, v228
	s_nop 3
	s_lshl_b32 s74, s74, 11
	s_add_u32 s30, s30, s69
	s_addc_u32 s31, s31, s70
	s_lshl_b32 s69, s28, 14
	s_add_u32 s34, s34, s69
	s_addc_u32 s35, s35, 0
	s_mov_b32 m0, 0x21e40
	s_nop 0
	global_load_lds_dwordx4 v226, s[30:31]
	s_add_u32 m0, s74, 0x22340
	s_nop 0
	global_load_lds_dwordx4 v227, s[34:35]
	global_load_lds_dwordx4 v227, s[34:35] offset:1024
	s_lshl_b32 s69, 1, s68
	s_movk_i32 s70, 25
	s_and_b32 s71, s69, 0x4
	s_cselect_b32 s70, 27, s70
	s_and_b32 s71, s69, 0x80
	s_cselect_b32 s70, 33, s70
	s_and_b32 s71, s69, 0x100
	s_cselect_b32 s70, 35, s70
	s_add_i32 s71, s70, 1
	s_nop 3
	v_readlane_b32 s30, v254, s70
	v_readlane_b32 s31, v254, s71
	s_lshl_b32 s69, s29, 8
	s_nop 3
	s_add_u32 s30, s30, s69
	s_addc_u32 s31, s31, 0
	s_mov_b64 s[34:35], exec
	s_mov_b64 exec, 0xffff
	s_mov_b32 m0, 0x22240
	s_nop 0
	global_load_lds_dwordx4 v226, s[30:31]
	s_mov_b64 exec, s[34:35]
	v_mov_b32_e32 v40, v251
	v_mov_b32_e32 v11, 1
	v_ashrrev_i32_e32 v0, 31, v40
	v_lshrrev_b32_e32 v0, 26, v0
	v_add_u32_e32 v0, v40, v0
	v_ashrrev_i32_e32 v2, 6, v0
	v_bfe_i32 v0, v40, 27, 1
	v_lshlrev_b32_e32 v41, 4, v40
	v_lshrrev_b32_e32 v0, 22, v0
	v_add_u32_e32 v0, v41, v0
	v_and_b32_e32 v0, 0xfffffc00, v0
	v_sub_u32_e32 v0, v41, v0
	v_lshrrev_b32_e32 v3, 4, v0
	v_bitop3_b32 v4, v3, v0, 32 bitop3:0x6c
	v_ashrrev_i32_e32 v0, 31, v0
	v_lshrrev_b32_e32 v0, 26, v0
	v_lshlrev_b32_e32 v3, 3, v2
	v_add_u32_e32 v0, v4, v0
	v_and_b32_e32 v5, 0x1ffff0, v3
	v_ashrrev_i32_e32 v3, 6, v0
	v_mul_i32_i24_e32 v6, 64, v3
	v_sub_u32_e32 v4, v4, v6
	v_lshlrev_b32_e32 v0, 5, v2
	v_ashrrev_i16_sdwa v4, v11, sext(v4) dst_sel:DWORD dst_unused:UNUSED_PAD src0_sel:DWORD src1_sel:BYTE_0
	v_and_b32_e32 v0, 32, v0
	v_bfe_i32 v4, v4, 0, 16
	v_add_u32_e32 v0, v0, v4
	v_add_lshl_u32 v5, v3, v5, 11
	v_add_u32_e32 v42, 0x2000, v41
	v_lshl_add_u32 v0, v0, 1, v5
	v_ashrrev_i32_e32 v5, 31, v42
	v_lshrrev_b32_e32 v5, 22, v5
	v_add_u32_e32 v5, v42, v5
	v_ashrrev_i32_e32 v5, 10, v5
	v_mul_i32_i24_e32 v6, 0x400, v5
	v_sub_u32_e32 v6, v42, v6
	s_lshl_b32 s2, s28, 8
	v_lshrrev_b32_e32 v7, 4, v6
	v_bitop3_b32 v7, v7, v6, 32 bitop3:0x6c
	v_lshlrev_b32_e32 v6, 3, v5
	s_ashr_i32 s3, s2, 31
	v_readlane_b32 s36, v254, 41
	s_lshl_b32 s10, s68, 8
	v_and_b32_e32 v8, 0x1ffff0, v6
	v_ashrrev_i32_e32 v6, 31, v7
	s_lshl_b64 s[4:5], s[2:3], 11
	v_readlane_b32 s42, v254, 47
	v_lshrrev_b32_e32 v6, 26, v6
	v_readlane_b32 s43, v254, 48
	s_add_u32 s4, s42, s4
	v_add_u32_e32 v9, v7, v6
	s_addc_u32 s5, s43, s5
	s_bitset1_b32 s2, 7
	v_ashrrev_i32_e32 v6, 6, v9
	v_and_b32_e32 v9, 0xc0, v9
	s_ashr_i32 s3, s2, 31
	v_sub_u32_e32 v7, v7, v9
	s_lshl_b64 s[2:3], s[2:3], 11
	v_lshlrev_b32_e32 v10, 5, v5
	v_ashrrev_i16_sdwa v7, v11, sext(v7) dst_sel:DWORD dst_unused:UNUSED_PAD src0_sel:DWORD src1_sel:BYTE_0
	v_add_u32_e32 v43, 0x10000, v41
	s_add_u32 s6, s42, s2
	v_and_b32_e32 v10, 32, v10
	v_bfe_i32 v7, v7, 0, 16
	v_readfirstlane_b32 s0, v43
	v_add_u32_e32 v44, 0x12000, v41
	s_addc_u32 s7, s43, s3
	s_ashr_i32 s11, s10, 31
	v_add_u32_e32 v9, v10, v7
	v_add_lshl_u32 v8, v6, v8, 11
	s_mov_b32 m0, s0
	v_readfirstlane_b32 s0, v44
	v_add_u32_e32 v45, 0x14000, v41
	s_lshl_b64 s[12:13], s[10:11], 11
	v_lshl_add_u32 v34, v9, 1, v8
	global_load_lds_dwordx4 v0, s[4:5]
	s_mov_b32 m0, s0
	v_readfirstlane_b32 s0, v45
	v_add_u32_e32 v46, 0x16000, v41
	s_add_u32 s8, s27, s12
	global_load_lds_dwordx4 v34, s[4:5]
	s_mov_b32 m0, s0
	v_readfirstlane_b32 s0, v46
	s_addc_u32 s9, s61, s13
	s_or_b32 s2, s10, 0x80
	global_load_lds_dwordx4 v0, s[6:7]
	s_mov_b32 m0, s0
	v_readfirstlane_b32 s0, v41
	s_ashr_i32 s3, s2, 31
	global_load_lds_dwordx4 v34, s[6:7]
	s_mov_b32 m0, s0
	v_readfirstlane_b32 s0, v42
	s_lshl_b64 s[2:3], s[2:3], 11
	v_add_u32_e32 v47, 0x4000, v41
	global_load_lds_dwordx4 v0, s[8:9]
	s_mov_b32 m0, s0
	s_add_u32 s10, s27, s2
	v_readfirstlane_b32 s0, v47
	v_add_u32_e32 v48, 0x6000, v41
	global_load_lds_dwordx4 v34, s[8:9]
	s_addc_u32 s11, s61, s3
	s_mov_b32 m0, s0
	v_readfirstlane_b32 s0, v48
	global_load_lds_dwordx4 v0, s[10:11]
	s_mov_b32 m0, s0
	v_ashrrev_i32_e32 v8, 8, v40
	global_load_lds_dwordx4 v34, s[10:11]
	v_cmp_eq_u32_e32 vcc, 1, v8
	v_readlane_b32 s37, v254, 42
	v_readlane_b32 s38, v254, 43
	v_readlane_b32 s39, v254, 44
	v_readlane_b32 s40, v254, 45
	v_readlane_b32 s41, v254, 46
	v_readlane_b32 s44, v254, 49
	v_readlane_b32 s45, v254, 50
	v_readlane_b32 s46, v254, 51
	v_readlane_b32 s47, v254, 52
	v_readlane_b32 s48, v254, 53
	v_readlane_b32 s49, v254, 54
	v_readlane_b32 s50, v254, 55
	v_readlane_b32 s51, v254, 56
	s_and_saveexec_b64 s[2:3], vcc
	s_cbranch_execz .LBB0_352
	s_barrier

; DI void phaseA_tile(const Params& p0, int l, int ft, int mt, char* lds) {
;     ...
;   float rstd[4];
; #pragma unroll
;   for (int gp = 0; gp < 2; ++gp) {
;     f32x4 sq[2][4];
; #pragma unroll
;     for (int n = 0; n < 2; ++n) {
;       const f32x4* sp = (const f32x4*)(p.ssq + (size_t)(m0 + tl[gp * 2 + n]) * 16);
; #pragma unroll
;       for (int q = 0; q < 4; ++q) sq[n][q] = sp[q];
;     }
; #pragma unroll
;     for (int n = 0; n < 2; ++n) {
;       float ss = 0.f;
; #pragma unroll
;       for (int q = 0; q < 4; ++q) ss += (sq[n][q][0] + sq[n][q][1]) + (sq[n][q][2] + sq[n][q][3]);
;       rstd[gp * 2 + n] = rsqrtf(ss * (1.f / DM) + EPS);
;     }
;   }
; #pragma unroll
;   for (int ai = 0; ai < 2; ++ai) {
;     const int f0 = n0 + ai * 128 + wr * 64;
;     const int hd = f0 >> 6;
;     int kind = 0; const float* gain = p.att_q_gain; bool do_rope = false; bool do_scale = false;
;     bf16_t* vtb = nullptr;
;     if (hd < 8) { kind = 2; gain = p.att_q_gain + l * 64; do_rope = !is_ctx; do_scale = true; }
;     else if (hd < 10) { kind = 2; gain = p.att_k_gain + l * 64; do_rope = !is_ctx; }
;     else if (hd < 12) { kind = 3; vtb = p.VtA + (size_t)((b * 2 + (hd - 10)) * 64) * KEYS; }
;     else if (hd < 20) { kind = 1; }
;     else if (hd < 24) { kind = 0; }
;     else if (hd < 28) { kind = 1; }
;     else if (hd < 32) { kind = 2; gain = p.na_q_gain + l * 64; do_scale = true; }
;     else if (hd < 36) { kind = 2; gain = p.na_k_gain + l * 64; }
;     else if (hd < 40) { kind = 3; vtb = p.VtN + (size_t)((b * 4 + (hd - 36)) * 64) * KEYS; }
;     else { kind = 1; }
;     f32x4 bv[4];
; #pragma unroll
;     for (int m = 0; m < 4; ++m) bv[m] = bvA[ai][m];
;     const float sc = do_scale ? 0.125f * LOG2E : 1.f;
;     ...
;             f32x4 cs4[2][2];
;             const int s = s_base + tl[gp * 2 + n];
; #pragma unroll
;             for (int hf = 0; hf < 2; ++hf) {
;               const int pos = hf == 0 ? (s >> 6) : (s & 63);
;               const float* tb = p.rope + (size_t)pos * 32 + fq * 8;
;               cs4[hf][0] = *(const f32x4*)(tb);
;               cs4[hf][1] = *(const f32x4*)(tb + 4);
;             }
.LBB0_356:
	s_or_b64 exec, exec, s[2:3]
	v_readlane_b32 s38, v255, 3
	s_barrier
	v_readlane_b32 s8, v254, 49
	v_readlane_b32 s9, v254, 50
	v_readlane_b32 s10, v254, 51
	v_readlane_b32 s11, v254, 52
	v_readlane_b32 s34, v254, 53
	v_readlane_b32 s35, v254, 54
	v_readlane_b32 s6, v254, 57
	v_readlane_b32 s7, v254, 58
	s_lshl_b32 s0, s28, 8
	s_lshl_b32 s30, s68, 8
	s_lshr_b32 s2, s28, 3
	s_sub_i32 s3, s28, 0x80
	s_and_b32 s69, s28, 7
	s_lshl_b32 s69, s69, 8
	s_cmpk_lt_i32 s28, 0x80
	s_cselect_b32 s39, s2, s3
	s_cselect_b32 s2, s2, 16
	s_cselect_b32 s69, s69, 0
	s_cselect_b32 s74, 0, 0x800
	s_cselect_b32 s42, 1, 0
	s_lshl_b32 s3, 1, s68
	s_mov_b32 s40, 1
	s_mov_b32 s41, 1
	s_and_b32 s70, s3, 0x187
	s_cselect_b32 s40, 2, s40
	s_and_b32 s70, s3, 0x200
	s_cselect_b32 s40, 3, s40
	s_and_b32 s70, s3, 0x20
	s_cselect_b32 s40, 0, s40
	s_and_b32 s70, s3, 0x183
	s_cselect_b32 s41, 2, s41
	s_and_b32 s70, s3, 0x204
	s_cselect_b32 s41, 3, s41
	s_and_b32 s70, s3, 0x20
	s_cselect_b32 s41, 0, s41
	s_and_b32 s70, s3, 0x7
	s_cselect_b32 s42, s42, 0
	s_mov_b32 s43, 1.0
	s_and_b32 s70, s3, 0x83
	s_cselect_b32 s43, 0x3e38aa3b, s43
	s_waitcnt lgkmcnt(0)
	s_lshl_b32 s2, s69, 1
	s_add_u32 s46, s6, s2
	s_addc_u32 s47, s7, 0
	v_and_b32_e32 v114, 15, v251
	v_bfe_u32 v115, v251, 4, 2
	v_bfe_u32 v116, v251, 6, 2
	v_lshrrev_b32_e32 v117, 8, v251
	v_lshlrev_b32_e32 v140, 4, v115
	v_lshl_add_u32 v137, v117, 8, v140
	v_add_u32_e32 v137, 0x21e40, v137
	v_lshl_add_u32 v118, v116, 5, v114
	v_lshl_add_u32 v138, v118, 6, v140
	v_add_u32_e32 v138, 0x22340, v138
	v_add_u32_e32 v140, 0x22240, v140
	v_lshrrev_b32_e32 v119, 1, v116
	v_lshlrev_b32_e32 v120, 5, v115
	v_lshl_add_u32 v141, v119, 7, v120
	v_and_b32_e32 v119, 1, v116
	v_lshl_add_u32 v119, v119, 5, v114
	v_lshl_add_u32 v142, v119, 7, v120
	v_lshrrev_b32_e32 v119, 1, v115
	v_lshl_or_b32 v119, v117, 3, v119
	v_xor_b32_e32 v119, v119, v114
	v_lshlrev_b32_e32 v119, 4, v119
	v_and_b32_e32 v120, 1, v115
	v_lshl_or_b32 v119, v120, 3, v119
	v_lshl_add_u32 v130, v118, 9, v119
	v_xor_b32_e32 v131, 32, v130
	v_xor_b32_e32 v132, 64, v130
	v_xor_b32_e32 v133, 96, v130
	v_and_b32_e32 v119, 3, v114
	v_and_b32_e32 v120, 4, v114
	v_lshl_or_b32 v119, v120, 1, v119
	v_and_b32_e32 v120, 8, v114
	v_lshrrev_b32_e32 v120, 1, v120
	v_or_b32_e32 v119, v119, v120
	v_lshl_add_u32 v119, v116, 5, v119
	v_lshlrev_b32_e32 v119, 1, v119
	v_mul_u32_u24_e32 v120, 0x4800, v115
	v_mul_u32_u24_e32 v121, 0x48000, v117
	v_add3_u32 v134, v119, v120, v121
	v_xor_b32_e32 v135, 16, v240
	v_lshlrev_b32_e32 v135, 2, v135
	v_xor_b32_e32 v136, 32, v240
	v_lshlrev_b32_e32 v136, 2, v136
	ds_read_b128 v[34:37], v137 offset:0
	ds_read_b128 v[38:41], v137 offset:64
	ds_read_b128 v[42:45], v137 offset:128
	ds_read_b128 v[46:49], v137 offset:192
	ds_read_b128 v[146:149], v137 offset:512
	ds_read_b128 v[150:153], v137 offset:576
	ds_read_b128 v[154:157], v137 offset:640
	ds_read_b128 v[158:161], v137 offset:704
	ds_read_b128 v[114:117], v138 offset:0
	ds_read_b128 v[118:121], v138 offset:1024
	ds_read_b128 v[122:125], v138 offset:8192
	ds_read_b128 v[126:129], v138 offset:9216
	ds_read_b128 v[194:197], v140
	ds_read_b128 v[198:201], v140 offset:64
	ds_read_b128 v[202:205], v140 offset:128
	ds_read_b128 v[206:209], v140 offset:192
	s_cmp_eq_u32 s42, 0
	s_cbranch_scc1 .Lea_norope
	global_load_dwordx4 v[210:213], v141, s[46:47] offset:0
	global_load_dwordx4 v[214:217], v141, s[46:47] offset:16
	global_load_dwordx4 v[218:221], v141, s[46:47] offset:256
	global_load_dwordx4 v[222:225], v141, s[46:47] offset:272
	global_load_dwordx4 v[226:229], v142, s[6:7] offset:0
	global_load_dwordx4 v[230:233], v142, s[6:7] offset:16
	global_load_dwordx4 v[234:237], v142, s[6:7] offset:2048
	global_load_dwordx4 v[242:245], v142, s[6:7] offset:2064
.Lea_norope:
	s_waitcnt lgkmcnt(0)
	v_add_f32_e32 v114, v114, v115
	v_add_f32_e32 v116, v116, v117
	v_add_f32_e32 v118, v118, v119
	v_add_f32_e32 v120, v120, v121
	v_add_f32_e32 v122, v122, v123
	v_add_f32_e32 v124, v124, v125
	v_add_f32_e32 v126, v126, v127
	v_add_f32_e32 v128, v128, v129
	v_add_f32_e32 v143, v114, v116
	v_add_f32_e32 v144, v118, v120
	v_add_f32_e32 v145, v122, v124
	v_add_f32_e32 v239, v126, v128
	v_mov_b32_e32 v114, v143
	v_mov_b32_e32 v115, v144
	v_mov_b32_e32 v116, v145
	v_mov_b32_e32 v117, v239
	s_nop 1
	v_permlane16_swap_b32 v143, v114
	v_permlane16_swap_b32 v144, v115
	v_permlane16_swap_b32 v145, v116
	v_permlane16_swap_b32 v239, v117
	v_add_f32_e32 v143, v143, v114
	v_add_f32_e32 v144, v144, v115
	v_add_f32_e32 v145, v145, v116
	v_add_f32_e32 v239, v239, v117
	s_nop 0
	v_mov_b32_e32 v114, v143
	v_mov_b32_e32 v115, v144
	v_mov_b32_e32 v116, v145
	v_mov_b32_e32 v117, v239
	s_nop 1
	v_permlane32_swap_b32 v143, v114
	v_permlane32_swap_b32 v144, v115
	v_permlane32_swap_b32 v145, v116
	v_permlane32_swap_b32 v239, v117
	v_add_f32_e32 v143, v143, v114
	v_add_f32_e32 v144, v144, v115
	v_add_f32_e32 v145, v145, v116
	v_add_f32_e32 v239, v239, v117
	s_nop 0
	v_mov_b32_e32 v118, 0x358637bd
	s_mov_b32 s2, 0x3a800000
	s_mov_b32 s3, 0x800000
	v_fma_f32 v143, v143, s2, v118
	v_fma_f32 v144, v144, s2, v118
	v_fma_f32 v145, v145, s2, v118
	v_fma_f32 v239, v239, s2, v118
	v_mul_f32_e32 v119, 0x4b800000, v143
	v_cmp_gt_f32_e32 vcc, s3, v143
	s_nop 1
	v_cndmask_b32_e32 v119, v143, v119, vcc
	v_rsq_f32_e32 v119, v119
	s_nop 0
	v_mul_f32_e32 v0, 0x45800000, v119
	v_cndmask_b32_e32 v0, v119, v0, vcc
	v_mul_f32_e32 v120, 0x4b800000, v144
	v_cmp_gt_f32_e32 vcc, s3, v144
	s_nop 1
	v_cndmask_b32_e32 v120, v144, v120, vcc
	v_rsq_f32_e32 v120, v120
	s_nop 0
	v_mul_f32_e32 v238, 0x45800000, v120
	v_cndmask_b32_e32 v238, v120, v238, vcc
; DI float silu_f(float v) { return v * __builtin_amdgcn_rcpf(1.f + __expf(-v)); }
; DI void phaseA_tile(const Params& p0, int l, int ft, int mt, char* lds) {
;     ...
;     for (int gp = 0; gp < 2; ++gp) {
;       float v[2][4][4];
; #pragma unroll
;       for (int n = 0; n < 2; ++n)
; #pragma unroll
;         for (int m = 0; m < 4; ++m)
; #pragma unroll
;           for (int j = 0; j < 4; ++j) v[n][m][j] = acc[ai][gp][m][n][j] * rstd[gp * 2 + n] + bv[m][j];
;       if (kind == 1) {
; #pragma unroll
;         for (int n = 0; n < 2; ++n)
; #pragma unroll
;           for (int m = 0; m < 4; ++m)
; #pragma unroll
;             for (int j = 0; j < 4; ++j) v[n][m][j] = silu_f(v[n][m][j]);
	v_mul_f32_e32 v121, 0x4b800000, v145
	v_cmp_gt_f32_e32 vcc, s3, v145
	s_nop 1
	v_cndmask_b32_e32 v121, v145, v121, vcc
	v_rsq_f32_e32 v121, v121
	s_nop 0
	v_mul_f32_e32 v246, 0x45800000, v121
	v_cndmask_b32_e32 v246, v121, v246, vcc
	v_mul_f32_e32 v122, 0x4b800000, v239
	v_cmp_gt_f32_e32 vcc, s3, v239
	s_nop 1
	v_cndmask_b32_e32 v122, v239, v122, vcc
	v_rsq_f32_e32 v122, v122
	s_nop 0
	v_mul_f32_e32 v248, 0x45800000, v122
	v_cndmask_b32_e32 v248, v122, v248, vcc
	s_mov_b32 s70, 0xbfb8aa3b
	s_mov_b32 s71, 1.0
	v_pk_fma_f32 v[190:191], v[190:191], v[0:1], v[34:35] op_sel_hi:[1,0,1]
	v_pk_fma_f32 v[192:193], v[192:193], v[0:1], v[36:37] op_sel_hi:[1,0,1]
	v_pk_fma_f32 v[186:187], v[186:187], v[0:1], v[38:39] op_sel_hi:[1,0,1]
	v_pk_fma_f32 v[188:189], v[188:189], v[0:1], v[40:41] op_sel_hi:[1,0,1]
	v_pk_fma_f32 v[178:179], v[178:179], v[0:1], v[42:43] op_sel_hi:[1,0,1]
	v_pk_fma_f32 v[180:181], v[180:181], v[0:1], v[44:45] op_sel_hi:[1,0,1]
	v_pk_fma_f32 v[170:171], v[170:171], v[0:1], v[46:47] op_sel_hi:[1,0,1]
	v_pk_fma_f32 v[172:173], v[172:173], v[0:1], v[48:49] op_sel_hi:[1,0,1]
	v_pk_fma_f32 v[182:183], v[182:183], v[238:239], v[34:35] op_sel_hi:[1,0,1]
	v_pk_fma_f32 v[184:185], v[184:185], v[238:239], v[36:37] op_sel_hi:[1,0,1]
	v_pk_fma_f32 v[174:175], v[174:175], v[238:239], v[38:39] op_sel_hi:[1,0,1]
	v_pk_fma_f32 v[176:177], v[176:177], v[238:239], v[40:41] op_sel_hi:[1,0,1]
	v_pk_fma_f32 v[166:167], v[166:167], v[238:239], v[42:43] op_sel_hi:[1,0,1]
	v_pk_fma_f32 v[168:169], v[168:169], v[238:239], v[44:45] op_sel_hi:[1,0,1]
	v_pk_fma_f32 v[162:163], v[162:163], v[238:239], v[46:47] op_sel_hi:[1,0,1]
	v_pk_fma_f32 v[164:165], v[164:165], v[238:239], v[48:49] op_sel_hi:[1,0,1]
	s_cmp_eq_u32 s40, 1
	s_cbranch_scc0 .Lea_n1_00
	v_pk_mul_f32 v[114:115], v[190:191], s[70:71] op_sel_hi:[1,0]
	v_pk_mul_f32 v[116:117], v[192:193], s[70:71] op_sel_hi:[1,0]
	v_pk_mul_f32 v[118:119], v[186:187], s[70:71] op_sel_hi:[1,0]
	v_pk_mul_f32 v[120:121], v[188:189], s[70:71] op_sel_hi:[1,0]
	v_exp_f32_e32 v114, v114
	v_exp_f32_e32 v115, v115
	v_exp_f32_e32 v116, v116
	v_exp_f32_e32 v117, v117
	v_exp_f32_e32 v118, v118
	v_exp_f32_e32 v119, v119
	v_exp_f32_e32 v120, v120
	v_exp_f32_e32 v121, v121
	v_pk_add_f32 v[114:115], v[114:115], s[70:71] op_sel:[0,1] op_sel_hi:[1,1]
	v_pk_add_f32 v[116:117], v[116:117], s[70:71] op_sel:[0,1] op_sel_hi:[1,1]
	v_pk_add_f32 v[118:119], v[118:119], s[70:71] op_sel:[0,1] op_sel_hi:[1,1]
	v_pk_add_f32 v[120:121], v[120:121], s[70:71] op_sel:[0,1] op_sel_hi:[1,1]
	v_rcp_f32_e32 v114, v114
	v_rcp_f32_e32 v115, v115
	v_rcp_f32_e32 v116, v116
	v_rcp_f32_e32 v117, v117
	v_rcp_f32_e32 v118, v118
	v_rcp_f32_e32 v119, v119
	v_rcp_f32_e32 v120, v120
	v_rcp_f32_e32 v121, v121
	s_nop 0
	v_pk_mul_f32 v[190:191], v[190:191], v[114:115]
	v_pk_mul_f32 v[192:193], v[192:193], v[116:117]
	v_pk_mul_f32 v[186:187], v[186:187], v[118:119]
	v_pk_mul_f32 v[188:189], v[188:189], v[120:121]
	v_pk_mul_f32 v[114:115], v[178:179], s[70:71] op_sel_hi:[1,0]
	v_pk_mul_f32 v[116:117], v[180:181], s[70:71] op_sel_hi:[1,0]
	v_pk_mul_f32 v[118:119], v[170:171], s[70:71] op_sel_hi:[1,0]
	v_pk_mul_f32 v[120:121], v[172:173], s[70:71] op_sel_hi:[1,0]
	v_exp_f32_e32 v114, v114
	v_exp_f32_e32 v115, v115
	v_exp_f32_e32 v116, v116
	v_exp_f32_e32 v117, v117
	v_exp_f32_e32 v118, v118
	v_exp_f32_e32 v119, v119
	v_exp_f32_e32 v120, v120
	v_exp_f32_e32 v121, v121
	v_pk_add_f32 v[114:115], v[114:115], s[70:71] op_sel:[0,1] op_sel_hi:[1,1]
	v_pk_add_f32 v[116:117], v[116:117], s[70:71] op_sel:[0,1] op_sel_hi:[1,1]
	v_pk_add_f32 v[118:119], v[118:119], s[70:71] op_sel:[0,1] op_sel_hi:[1,1]
	v_pk_add_f32 v[120:121], v[120:121], s[70:71] op_sel:[0,1] op_sel_hi:[1,1]
	v_rcp_f32_e32 v114, v114
	v_rcp_f32_e32 v115, v115
	v_rcp_f32_e32 v116, v116
	v_rcp_f32_e32 v117, v117
	v_rcp_f32_e32 v118, v118
	v_rcp_f32_e32 v119, v119
	v_rcp_f32_e32 v120, v120
	v_rcp_f32_e32 v121, v121
	s_nop 0
	v_pk_mul_f32 v[178:179], v[178:179], v[114:115]
	v_pk_mul_f32 v[180:181], v[180:181], v[116:117]
	v_pk_mul_f32 v[170:171], v[170:171], v[118:119]
	v_pk_mul_f32 v[172:173], v[172:173], v[120:121]
	v_pk_mul_f32 v[114:115], v[182:183], s[70:71] op_sel_hi:[1,0]
	v_pk_mul_f32 v[116:117], v[184:185], s[70:71] op_sel_hi:[1,0]
	v_pk_mul_f32 v[118:119], v[174:175], s[70:71] op_sel_hi:[1,0]
	v_pk_mul_f32 v[120:121], v[176:177], s[70:71] op_sel_hi:[1,0]
	v_exp_f32_e32 v114, v114
	v_exp_f32_e32 v115, v115
	v_exp_f32_e32 v116, v116
	v_exp_f32_e32 v117, v117
	v_exp_f32_e32 v118, v118
	v_exp_f32_e32 v119, v119
	v_exp_f32_e32 v120, v120
	v_exp_f32_e32 v121, v121
	v_pk_add_f32 v[114:115], v[114:115], s[70:71] op_sel:[0,1] op_sel_hi:[1,1]
	v_pk_add_f32 v[116:117], v[116:117], s[70:71] op_sel:[0,1] op_sel_hi:[1,1]
	v_pk_add_f32 v[118:119], v[118:119], s[70:71] op_sel:[0,1] op_sel_hi:[1,1]
	v_pk_add_f32 v[120:121], v[120:121], s[70:71] op_sel:[0,1] op_sel_hi:[1,1]
	v_rcp_f32_e32 v114, v114
	v_rcp_f32_e32 v115, v115
	v_rcp_f32_e32 v116, v116
	v_rcp_f32_e32 v117, v117
	v_rcp_f32_e32 v118, v118
	v_rcp_f32_e32 v119, v119
	v_rcp_f32_e32 v120, v120
	v_rcp_f32_e32 v121, v121
	s_nop 0
	v_pk_mul_f32 v[182:183], v[182:183], v[114:115]
	v_pk_mul_f32 v[184:185], v[184:185], v[116:117]
	v_pk_mul_f32 v[174:175], v[174:175], v[118:119]
	v_pk_mul_f32 v[176:177], v[176:177], v[120:121]
	v_pk_mul_f32 v[114:115], v[166:167], s[70:71] op_sel_hi:[1,0]
	v_pk_mul_f32 v[116:117], v[168:169], s[70:71] op_sel_hi:[1,0]
	v_pk_mul_f32 v[118:119], v[162:163], s[70:71] op_sel_hi:[1,0]
	v_pk_mul_f32 v[120:121], v[164:165], s[70:71] op_sel_hi:[1,0]
	v_exp_f32_e32 v114, v114
	v_exp_f32_e32 v115, v115
	v_exp_f32_e32 v116, v116
	v_exp_f32_e32 v117, v117
	v_exp_f32_e32 v118, v118
	v_exp_f32_e32 v119, v119
	v_exp_f32_e32 v120, v120
	v_exp_f32_e32 v121, v121
	v_pk_add_f32 v[114:115], v[114:115], s[70:71] op_sel:[0,1] op_sel_hi:[1,1]
	v_pk_add_f32 v[116:117], v[116:117], s[70:71] op_sel:[0,1] op_sel_hi:[1,1]
	v_pk_add_f32 v[118:119], v[118:119], s[70:71] op_sel:[0,1] op_sel_hi:[1,1]
	v_pk_add_f32 v[120:121], v[120:121], s[70:71] op_sel:[0,1] op_sel_hi:[1,1]
	v_rcp_f32_e32 v114, v114
	v_rcp_f32_e32 v115, v115
	v_rcp_f32_e32 v116, v116
	v_rcp_f32_e32 v117, v117
	v_rcp_f32_e32 v118, v118
	v_rcp_f32_e32 v119, v119
	v_rcp_f32_e32 v120, v120
	v_rcp_f32_e32 v121, v121
	s_nop 0
	v_pk_mul_f32 v[166:167], v[166:167], v[114:115]
	v_pk_mul_f32 v[168:169], v[168:169], v[116:117]
	v_pk_mul_f32 v[162:163], v[162:163], v[118:119]
	v_pk_mul_f32 v[164:165], v[164:165], v[120:121]
	s_branch .Lea_pack_00
